# scan: y-reduction over 4 steps via bank-masked DPP adds (8 dpp) instead of cndmask butterfly (6 cndmask + 5 dpp)
# speedup vs baseline: 1.0875x; 1.0073x over previous
; DI void scan_task(const Params& P, int sb, unsigned char* lds) {
;     ...
;     const int q = lane & 15, q4 = q * 4, rowl = w * 4 + (lane >> 4);
;     const bool o1 = (lane & 1) != 0, o2 = (lane & 2) != 0;
;     ...
;         yb[(g4 * 4 + (q & 3)) * 16 + rowl] = u;
.LBB0_1193:
	s_andn2_b64 vcc, exec, s[4:5]
	s_cbranch_vccnz .LBB0_1235
	s_bitcmp0_b32 s76, 2
	s_cbranch_scc1 .LBB0_1235
	v_readfirstlane_b32 s1, v208
	s_cmpk_lt_u32 s1, 0x100
	s_mov_b64 s[4:5], -1
	s_waitcnt vmcnt(63) expcnt(7) lgkmcnt(15)
	s_barrier
	s_cbranch_scc0 .LBB0_1201
	v_lshlrev_b32_e32 v0, 2, v208
	v_and_b32_e32 v68, 60, v0
	v_and_b32_e32 v0, 1, v208
	s_and_b32 s3, s1, 0xc0
	v_cmp_eq_u32_e32 vcc, 0, v0
	v_and_b32_e32 v0, 2, v208
	v_and_b32_e32 v1, 15, v208
	v_mov_b32_e32 v2, 0x1080
	v_cmp_eq_u32_e64 s[4:5], 0, v0
	v_bfe_u32 v0, v208, 2, 2
	v_lshl_add_u32 v69, v1, 4, v2
	v_and_or_b32 v1, v208, 48, s3
	v_lshrrev_b32_e32 v1, 2, v1
	v_lshlrev_b32_e32 v0, 6, v0
	s_mov_b32 s3, 0x16000
	v_or3_b32 v70, v1, v0, s3
	s_lshl_b32 s1, s1, 3
	v_lshlrev_b32_e32 v0, 3, v208
	v_mov_b32_e32 v64, 0
	s_and_b32 s1, s1, 0x600
	v_and_b32_e32 v0, 0x180, v0
	v_mov_b32_e32 v65, v64
	s_mov_b32 s0, 0
	v_or_b32_e32 v71, s1, v0
	s_mov_b64 s[6:7], 0
	s_mov_b32 s1, 0xb000
	v_mov_b64_e32 v[66:67], v[64:65]
	s_barrier

; template <int CTRL> DI float dppf(float v) { return __int_as_float(__builtin_amdgcn_update_dpp(0, __float_as_int(v), CTRL, 0xf, 0xf, false)); }
; DI float red16(float p) { p += dppf<0xB1>(p); p += dppf<0x4E>(p); p += dppf<0x141>(p); p += dppf<0x140>(p); return p; }
; DI void scan_task(const Params& P, int sb, unsigned char* lds) {
;     ...
;       for (int g4 = 0; g4 < CH / 4; ++g4) {
;         const float* gb = cb + g4 * 4 * SREC;
;         const float4 v4 = *(const float4*)(vrow + g4 * 4);
;         float pp[4];
; #pragma unroll
;         for (int i = 0; i < 4; ++i) {
;           ld_ops(nx3, gb + (i + 3) * SREC, q4);
;           const f2 a01 = {cur.a.x, cur.a.y}, a23 = {cur.a.z, cur.a.w}, w01 = {cur.w.x, cur.w.y}, w23 = {cur.w.z, cur.w.w};
;           const f2 k01 = {cur.k.x, cur.k.y}, k23 = {cur.k.z, cur.k.w}, b01 = {cur.b.x, cur.b.y}, b23 = {cur.b.z, cur.b.w};
;           const f2 r01 = {cur.r.x, cur.r.y}, r23 = {cur.r.z, cur.r.w};
;           f2 pa = S0 * a01; pa += S1 * a23;
;           const float vs = (i == 0) ? v4.x : (i == 1) ? v4.y : (i == 2) ? v4.z : v4.w;
;           const f2 vv = {vs, vs};
;           const f2 t0 = S0 * w01 + vv * k01, t1 = S1 * w23 + vv * k23;
;           const float sa = red16(pa.x + pa.y);
;           const f2 sa2 = {sa, sa};
;           S0 = t0 + sa2 * b01; S1 = t1 + sa2 * b23;
;           f2 py = S0 * r01; py += S1 * r23;
;           pp[i] = py.x + py.y;
;           cur = nxt; nxt = nx2; nx2 = nx3;
;         }
;         const float tA = o1 ? pp[0] : pp[1], kA = o1 ? pp[1] : pp[0];
;         const float tB = o1 ? pp[2] : pp[3], kB = o1 ? pp[3] : pp[2];
;         const float r0 = kA + dppf<0xB1>(tA), r1 = kB + dppf<0xB1>(tB);
;         const float tC = o2 ? r0 : r1, kC = o2 ? r1 : r0;
;         float u = kC + dppf<0x4E>(tC);
;         u += dppf<0x124>(u);
;         u += dppf<0x128>(u);
;         yb[(g4 * 4 + (q & 3)) * 16 + rowl] = u;
;       }
.LBB0_1198:
	v_add_u32_e32 v100, 0x18000, v74
	s_waitcnt lgkmcnt(14)
	v_pk_mul_f32 v[2:3], v[64:65], v[2:3]
	ds_read_b128 v[60:63], v72 offset:256
	ds_read_b128 v[76:79], v72 offset:512
	ds_read_b128 v[80:83], v72 offset:768
	ds_read_b128 v[84:87], v72 offset:1024
	ds_read_b128 v[88:91], v100
	ds_read_b128 v[92:95], v72
	v_pk_fma_f32 v[96:97], v[66:67], v[0:1], v[2:3]
	ds_read_b128 v[0:3], v72 offset:1408
	v_add_f32_e32 v75, v96, v97
	s_waitcnt lgkmcnt(2)
	v_pk_mul_f32 v[14:15], v[14:15], v[88:89] op_sel_hi:[1,0]
	v_pk_mul_f32 v[12:13], v[12:13], v[88:89] op_sel_hi:[1,0]
	v_add_f32_dpp v75, v75, v75 quad_perm:[1,0,3,2] row_mask:0xf bank_mask:0xf bound_ctrl:1
	v_pk_fma_f32 v[64:65], v[64:65], v[10:11], v[14:15]
	v_pk_fma_f32 v[66:67], v[66:67], v[8:9], v[12:13]
	v_add_f32_dpp v75, v75, v75 quad_perm:[2,3,0,1] row_mask:0xf bank_mask:0xf bound_ctrl:1
	v_mov_b32_e32 v98, v91
	ds_read_b128 v[8:11], v72 offset:1920
	ds_read_b128 v[12:15], v72 offset:2176
	v_add_f32_dpp v75, v75, v75 row_half_mirror row_mask:0xf bank_mask:0xf bound_ctrl:1
	s_nop 1
	v_add_f32_dpp v96, v75, v75 row_mirror row_mask:0xf bank_mask:0xf bound_ctrl:1
	v_pk_fma_f32 v[64:65], v[6:7], v[96:97], v[64:65] op_sel_hi:[1,0,1]
	v_pk_fma_f32 v[66:67], v[4:5], v[96:97], v[66:67] op_sel_hi:[1,0,1]
	v_pk_mul_f32 v[18:19], v[18:19], v[64:65]
	v_pk_mul_f32 v[22:23], v[22:23], v[64:65]
	v_pk_mul_f32 v[36:37], v[36:37], v[66:67]
	v_pk_mul_f32 v[38:39], v[38:39], v[64:65]
	v_pk_fma_f32 v[64:65], v[16:17], v[66:67], v[18:19]
	v_pk_fma_f32 v[66:67], v[20:21], v[66:67], v[22:23]
	v_add_f32_e32 v75, v64, v65
	v_add_f32_e32 v64, v66, v67
	v_pk_fma_f32 v[36:37], v[28:29], v[88:89], v[36:37] op_sel:[0,1,0]
	v_pk_fma_f32 v[38:39], v[30:31], v[88:89], v[38:39] op_sel:[0,1,0]
	v_add_f32_dpp v64, v64, v64 quad_perm:[1,0,3,2] row_mask:0xf bank_mask:0xf bound_ctrl:1
	ds_read_b128 v[4:7], v72 offset:1664
	ds_read_b128 v[16:19], v72 offset:2432
	v_add_f32_dpp v64, v64, v64 quad_perm:[2,3,0,1] row_mask:0xf bank_mask:0xf bound_ctrl:1
	ds_read_b128 v[20:23], v72 offset:2816
	ds_read_b128 v[28:31], v72 offset:3584
	v_add_f32_dpp v64, v64, v64 row_half_mirror row_mask:0xf bank_mask:0xf bound_ctrl:1
	s_nop 1
	v_add_f32_dpp v64, v64, v64 row_mirror row_mask:0xf bank_mask:0xf bound_ctrl:1
	v_pk_fma_f32 v[66:67], v[24:25], v[64:65], v[36:37] op_sel_hi:[1,0,1]
	v_pk_fma_f32 v[64:65], v[26:27], v[64:65], v[38:39] op_sel_hi:[1,0,1]
	v_pk_mul_f32 v[88:89], v[48:49], v[66:67]
	v_pk_mul_f32 v[34:35], v[34:35], v[64:65]
	v_pk_mul_f32 v[42:43], v[42:43], v[64:65]
	v_pk_fma_f32 v[96:97], v[32:33], v[66:67], v[34:35]
	v_pk_fma_f32 v[66:67], v[40:41], v[66:67], v[42:43]
	v_pk_mul_f32 v[64:65], v[50:51], v[64:65]
	v_add_f32_e32 v66, v66, v67
	v_pk_fma_f32 v[88:89], v[52:53], v[90:91], v[88:89] op_sel_hi:[1,0,1]
	v_pk_fma_f32 v[64:65], v[54:55], v[90:91], v[64:65] op_sel_hi:[1,0,1]
	v_add_f32_dpp v66, v66, v66 quad_perm:[1,0,3,2] row_mask:0xf bank_mask:0xf bound_ctrl:1
	v_add_f32_e32 v90, v96, v97
	v_add_f32_dpp v105, v75, v75 row_ror:8 row_mask:0xf bank_mask:0x3 bound_ctrl:1
	v_add_f32_dpp v66, v66, v66 quad_perm:[2,3,0,1] row_mask:0xf bank_mask:0xf bound_ctrl:1
	v_add_f32_dpp v107, v90, v90 row_ror:8 row_mask:0xf bank_mask:0x3 bound_ctrl:1
	ds_read_b128 v[24:27], v72 offset:3072
	ds_read_b128 v[36:39], v72 offset:3328
	v_add_f32_dpp v66, v66, v66 row_half_mirror row_mask:0xf bank_mask:0xf bound_ctrl:1
	ds_read_b128 v[48:51], v72 offset:4736
	ds_read_b128 v[32:35], v72 offset:3840
	v_add_f32_dpp v66, v66, v66 row_mirror row_mask:0xf bank_mask:0xf bound_ctrl:1
	v_pk_fma_f32 v[64:65], v[46:47], v[66:67], v[64:65] op_sel_hi:[1,0,1]
	v_pk_fma_f32 v[88:89], v[44:45], v[66:67], v[88:89] op_sel_hi:[1,0,1]
	s_waitcnt lgkmcnt(11)
	v_pk_mul_f32 v[66:67], v[94:95], v[64:65]
	v_pk_mul_f32 v[58:59], v[58:59], v[64:65]
	v_pk_fma_f32 v[66:67], v[92:93], v[88:89], v[66:67]
	v_pk_mul_f32 v[64:65], v[78:79], v[64:65]
	v_add_f32_e32 v66, v66, v67
	v_pk_fma_f32 v[78:79], v[56:57], v[88:89], v[58:59]
	v_pk_mul_f32 v[76:77], v[76:77], v[88:89]
	v_add_f32_dpp v66, v66, v66 quad_perm:[1,0,3,2] row_mask:0xf bank_mask:0xf bound_ctrl:1
	v_pk_fma_f32 v[64:65], v[98:99], v[82:83], v[64:65] op_sel_hi:[0,1,1]
	v_add_f32_e32 v104, v78, v79
	v_add_f32_dpp v66, v66, v66 quad_perm:[2,3,0,1] row_mask:0xf bank_mask:0xf bound_ctrl:1
	v_pk_fma_f32 v[76:77], v[98:99], v[80:81], v[76:77] op_sel_hi:[0,1,1]
	ds_read_b128 v[40:43], v72 offset:4224
	ds_read_b128 v[52:55], v72 offset:4992
	v_add_f32_dpp v66, v66, v66 row_half_mirror row_mask:0xf bank_mask:0xf bound_ctrl:1
	ds_read_b128 v[44:47], v72 offset:4480
	ds_read_b128 v[56:59], v72 offset:5248
	v_add_f32_dpp v78, v66, v66 row_mirror row_mask:0xf bank_mask:0xf bound_ctrl:1
	v_pk_fma_f32 v[64:65], v[62:63], v[78:79], v[64:65] op_sel_hi:[1,0,1]
	v_pk_fma_f32 v[66:67], v[60:61], v[78:79], v[76:77] op_sel_hi:[1,0,1]
	v_pk_mul_f32 v[102:103], v[86:87], v[64:65]
	v_pk_fma_f32 v[102:103], v[84:85], v[66:67], v[102:103]
	s_waitcnt lgkmcnt(14)
	v_pk_mul_f32 v[2:3], v[64:65], v[2:3]
	v_add_f32_e32 v102, v102, v103
	ds_read_b128 v[60:63], v72 offset:5888
	v_add_f32_dpp v105, v104, v104 row_ror:8 row_mask:0xf bank_mask:0xc bound_ctrl:1
	ds_read_b128 v[76:79], v72 offset:6144
	ds_read_b128 v[80:83], v72 offset:6400
	ds_read_b128 v[84:87], v72 offset:6656
	ds_read_b128 v[88:91], v100 offset:16
	ds_read_b128 v[92:95], v72 offset:5632
	v_add_f32_dpp v107, v102, v102 row_ror:8 row_mask:0xf bank_mask:0xc bound_ctrl:1
	v_pk_fma_f32 v[96:97], v[66:67], v[0:1], v[2:3]
	v_add_f32_dpp v108, v105, v105 row_half_mirror row_mask:0xf bank_mask:0x5 bound_ctrl:1
	v_add_f32_dpp v108, v107, v107 row_half_mirror row_mask:0xf bank_mask:0xa bound_ctrl:1
	ds_read_b128 v[0:3], v72 offset:7040
	v_add_f32_e32 v75, v96, v97
	s_waitcnt lgkmcnt(2)
; template <int CTRL> DI float dppf(float v) { return __int_as_float(__builtin_amdgcn_update_dpp(0, __float_as_int(v), CTRL, 0xf, 0xf, false)); }
; DI float red16(float p) { p += dppf<0xB1>(p); p += dppf<0x4E>(p); p += dppf<0x141>(p); p += dppf<0x140>(p); return p; }
; DI void scan_task(const Params& P, int sb, unsigned char* lds) {
;     ...
;       for (int g4 = 0; g4 < CH / 4; ++g4) {
;         const float* gb = cb + g4 * 4 * SREC;
;         const float4 v4 = *(const float4*)(vrow + g4 * 4);
;         float pp[4];
; #pragma unroll
;         for (int i = 0; i < 4; ++i) {
;           ld_ops(nx3, gb + (i + 3) * SREC, q4);
;           const f2 a01 = {cur.a.x, cur.a.y}, a23 = {cur.a.z, cur.a.w}, w01 = {cur.w.x, cur.w.y}, w23 = {cur.w.z, cur.w.w};
;           const f2 k01 = {cur.k.x, cur.k.y}, k23 = {cur.k.z, cur.k.w}, b01 = {cur.b.x, cur.b.y}, b23 = {cur.b.z, cur.b.w};
;           const f2 r01 = {cur.r.x, cur.r.y}, r23 = {cur.r.z, cur.r.w};
;           f2 pa = S0 * a01; pa += S1 * a23;
;           const float vs = (i == 0) ? v4.x : (i == 1) ? v4.y : (i == 2) ? v4.z : v4.w;
;           const f2 vv = {vs, vs};
;           const f2 t0 = S0 * w01 + vv * k01, t1 = S1 * w23 + vv * k23;
;           const float sa = red16(pa.x + pa.y);
;           const f2 sa2 = {sa, sa};
;           S0 = t0 + sa2 * b01; S1 = t1 + sa2 * b23;
;           f2 py = S0 * r01; py += S1 * r23;
;           pp[i] = py.x + py.y;
;           cur = nxt; nxt = nx2; nx2 = nx3;
;         }
;         const float tA = o1 ? pp[0] : pp[1], kA = o1 ? pp[1] : pp[0];
;         const float tB = o1 ? pp[2] : pp[3], kB = o1 ? pp[3] : pp[2];
;         const float r0 = kA + dppf<0xB1>(tA), r1 = kB + dppf<0xB1>(tB);
;         const float tC = o2 ? r0 : r1, kC = o2 ? r1 : r0;
;         float u = kC + dppf<0x4E>(tC);
;         u += dppf<0x124>(u);
;         u += dppf<0x128>(u);
;         yb[(g4 * 4 + (q & 3)) * 16 + rowl] = u;
;       }
	v_add_f32_dpp v108, v108, v108 quad_perm:[1,0,3,2] row_mask:0xf bank_mask:0xf bound_ctrl:1
	v_pk_mul_f32 v[14:15], v[14:15], v[88:89] op_sel_hi:[1,0]
	v_pk_mul_f32 v[12:13], v[12:13], v[88:89] op_sel_hi:[1,0]
	v_add_f32_dpp v108, v108, v108 quad_perm:[2,3,0,1] row_mask:0xf bank_mask:0xf bound_ctrl:1
	v_add_f32_dpp v75, v75, v75 quad_perm:[1,0,3,2] row_mask:0xf bank_mask:0xf bound_ctrl:1
	v_pk_fma_f32 v[64:65], v[64:65], v[10:11], v[14:15]
	v_pk_fma_f32 v[66:67], v[66:67], v[8:9], v[12:13]
	v_add_f32_dpp v75, v75, v75 quad_perm:[2,3,0,1] row_mask:0xf bank_mask:0xf bound_ctrl:1
	v_mov_b32_e32 v98, v91
	ds_write_b32 v73, v108
	v_add_f32_dpp v75, v75, v75 row_half_mirror row_mask:0xf bank_mask:0xf bound_ctrl:1
	ds_read_b128 v[8:11], v72 offset:7552
	ds_read_b128 v[12:15], v72 offset:7808
	v_add_f32_dpp v96, v75, v75 row_mirror row_mask:0xf bank_mask:0xf bound_ctrl:1
	v_pk_fma_f32 v[64:65], v[6:7], v[96:97], v[64:65] op_sel_hi:[1,0,1]
	v_pk_fma_f32 v[66:67], v[4:5], v[96:97], v[66:67] op_sel_hi:[1,0,1]
	v_pk_mul_f32 v[18:19], v[18:19], v[64:65]
	v_pk_mul_f32 v[22:23], v[22:23], v[64:65]
	v_pk_mul_f32 v[36:37], v[36:37], v[66:67]
	v_pk_mul_f32 v[38:39], v[38:39], v[64:65]
	v_pk_fma_f32 v[64:65], v[16:17], v[66:67], v[18:19]
	v_pk_fma_f32 v[66:67], v[20:21], v[66:67], v[22:23]
	v_add_f32_e32 v75, v64, v65
	v_add_f32_e32 v64, v66, v67
	v_pk_fma_f32 v[36:37], v[28:29], v[88:89], v[36:37] op_sel:[0,1,0]
	v_pk_fma_f32 v[38:39], v[30:31], v[88:89], v[38:39] op_sel:[0,1,0]
	v_add_f32_dpp v64, v64, v64 quad_perm:[1,0,3,2] row_mask:0xf bank_mask:0xf bound_ctrl:1
	ds_read_b128 v[4:7], v72 offset:7296
	ds_read_b128 v[16:19], v72 offset:8064
	v_add_f32_dpp v64, v64, v64 quad_perm:[2,3,0,1] row_mask:0xf bank_mask:0xf bound_ctrl:1
	ds_read_b128 v[20:23], v72 offset:8448
	ds_read_b128 v[28:31], v72 offset:9216
	v_add_f32_dpp v64, v64, v64 row_half_mirror row_mask:0xf bank_mask:0xf bound_ctrl:1
	s_nop 1
	v_add_f32_dpp v64, v64, v64 row_mirror row_mask:0xf bank_mask:0xf bound_ctrl:1
	v_pk_fma_f32 v[66:67], v[24:25], v[64:65], v[36:37] op_sel_hi:[1,0,1]
	v_pk_fma_f32 v[64:65], v[26:27], v[64:65], v[38:39] op_sel_hi:[1,0,1]
	v_pk_mul_f32 v[88:89], v[48:49], v[66:67]
	v_pk_mul_f32 v[34:35], v[34:35], v[64:65]
	v_pk_mul_f32 v[42:43], v[42:43], v[64:65]
	v_pk_fma_f32 v[96:97], v[32:33], v[66:67], v[34:35]
	v_pk_fma_f32 v[66:67], v[40:41], v[66:67], v[42:43]
	v_pk_mul_f32 v[64:65], v[50:51], v[64:65]
	v_add_f32_e32 v66, v66, v67
	v_pk_fma_f32 v[88:89], v[52:53], v[90:91], v[88:89] op_sel_hi:[1,0,1]
	v_pk_fma_f32 v[64:65], v[54:55], v[90:91], v[64:65] op_sel_hi:[1,0,1]
	v_add_f32_dpp v66, v66, v66 quad_perm:[1,0,3,2] row_mask:0xf bank_mask:0xf bound_ctrl:1
	v_add_f32_e32 v90, v96, v97
	v_add_f32_dpp v105, v75, v75 row_ror:8 row_mask:0xf bank_mask:0x3 bound_ctrl:1
	v_add_f32_dpp v66, v66, v66 quad_perm:[2,3,0,1] row_mask:0xf bank_mask:0xf bound_ctrl:1
	v_add_f32_dpp v107, v90, v90 row_ror:8 row_mask:0xf bank_mask:0x3 bound_ctrl:1
	ds_read_b128 v[24:27], v72 offset:8704
	ds_read_b128 v[36:39], v72 offset:8960
	v_add_f32_dpp v66, v66, v66 row_half_mirror row_mask:0xf bank_mask:0xf bound_ctrl:1
	ds_read_b128 v[48:51], v72 offset:10368
	ds_read_b128 v[32:35], v72 offset:9472
	v_add_f32_dpp v66, v66, v66 row_mirror row_mask:0xf bank_mask:0xf bound_ctrl:1
	v_pk_fma_f32 v[64:65], v[46:47], v[66:67], v[64:65] op_sel_hi:[1,0,1]
	v_pk_fma_f32 v[88:89], v[44:45], v[66:67], v[88:89] op_sel_hi:[1,0,1]
	s_waitcnt lgkmcnt(11)
	v_pk_mul_f32 v[66:67], v[94:95], v[64:65]
	v_pk_mul_f32 v[58:59], v[58:59], v[64:65]
	v_pk_fma_f32 v[66:67], v[92:93], v[88:89], v[66:67]
	v_pk_mul_f32 v[64:65], v[78:79], v[64:65]
	v_add_f32_e32 v66, v66, v67
	v_pk_fma_f32 v[78:79], v[56:57], v[88:89], v[58:59]
	v_pk_mul_f32 v[76:77], v[76:77], v[88:89]
	v_add_f32_dpp v66, v66, v66 quad_perm:[1,0,3,2] row_mask:0xf bank_mask:0xf bound_ctrl:1
	v_pk_fma_f32 v[64:65], v[98:99], v[82:83], v[64:65] op_sel_hi:[0,1,1]
	v_add_f32_e32 v104, v78, v79
	v_add_f32_dpp v66, v66, v66 quad_perm:[2,3,0,1] row_mask:0xf bank_mask:0xf bound_ctrl:1
	v_pk_fma_f32 v[76:77], v[98:99], v[80:81], v[76:77] op_sel_hi:[0,1,1]
	ds_read_b128 v[40:43], v72 offset:9856
	ds_read_b128 v[52:55], v72 offset:10624
	v_add_f32_dpp v66, v66, v66 row_half_mirror row_mask:0xf bank_mask:0xf bound_ctrl:1
	ds_read_b128 v[44:47], v72 offset:10112
	ds_read_b128 v[56:59], v72 offset:10880
	v_add_f32_dpp v78, v66, v66 row_mirror row_mask:0xf bank_mask:0xf bound_ctrl:1
	v_pk_fma_f32 v[64:65], v[62:63], v[78:79], v[64:65] op_sel_hi:[1,0,1]
	v_pk_fma_f32 v[66:67], v[60:61], v[78:79], v[76:77] op_sel_hi:[1,0,1]
	v_pk_mul_f32 v[102:103], v[86:87], v[64:65]
	v_pk_fma_f32 v[102:103], v[84:85], v[66:67], v[102:103]
	s_waitcnt lgkmcnt(14)
	v_pk_mul_f32 v[2:3], v[64:65], v[2:3]
	v_add_f32_e32 v102, v102, v103
	ds_read_b128 v[60:63], v72 offset:11520
	v_add_f32_dpp v105, v104, v104 row_ror:8 row_mask:0xf bank_mask:0xc bound_ctrl:1
	ds_read_b128 v[76:79], v72 offset:11776
	ds_read_b128 v[80:83], v72 offset:12032
	ds_read_b128 v[84:87], v72 offset:12288
	ds_read_b128 v[88:91], v100 offset:32
	ds_read_b128 v[92:95], v72 offset:11264
	v_add_f32_dpp v107, v102, v102 row_ror:8 row_mask:0xf bank_mask:0xc bound_ctrl:1
	v_pk_fma_f32 v[96:97], v[66:67], v[0:1], v[2:3]
	v_add_f32_dpp v108, v105, v105 row_half_mirror row_mask:0xf bank_mask:0x5 bound_ctrl:1
	v_add_f32_dpp v108, v107, v107 row_half_mirror row_mask:0xf bank_mask:0xa bound_ctrl:1
	ds_read_b128 v[0:3], v72 offset:12672
	v_add_f32_e32 v75, v96, v97
	s_waitcnt lgkmcnt(2)
; template <int CTRL> DI float dppf(float v) { return __int_as_float(__builtin_amdgcn_update_dpp(0, __float_as_int(v), CTRL, 0xf, 0xf, false)); }
; DI float red16(float p) { p += dppf<0xB1>(p); p += dppf<0x4E>(p); p += dppf<0x141>(p); p += dppf<0x140>(p); return p; }
; DI void scan_task(const Params& P, int sb, unsigned char* lds) {
;     ...
;       for (int g4 = 0; g4 < CH / 4; ++g4) {
;         const float* gb = cb + g4 * 4 * SREC;
;         const float4 v4 = *(const float4*)(vrow + g4 * 4);
;         float pp[4];
; #pragma unroll
;         for (int i = 0; i < 4; ++i) {
;           ld_ops(nx3, gb + (i + 3) * SREC, q4);
;           const f2 a01 = {cur.a.x, cur.a.y}, a23 = {cur.a.z, cur.a.w}, w01 = {cur.w.x, cur.w.y}, w23 = {cur.w.z, cur.w.w};
;           const f2 k01 = {cur.k.x, cur.k.y}, k23 = {cur.k.z, cur.k.w}, b01 = {cur.b.x, cur.b.y}, b23 = {cur.b.z, cur.b.w};
;           const f2 r01 = {cur.r.x, cur.r.y}, r23 = {cur.r.z, cur.r.w};
;           f2 pa = S0 * a01; pa += S1 * a23;
;           const float vs = (i == 0) ? v4.x : (i == 1) ? v4.y : (i == 2) ? v4.z : v4.w;
;           const f2 vv = {vs, vs};
;           const f2 t0 = S0 * w01 + vv * k01, t1 = S1 * w23 + vv * k23;
;           const float sa = red16(pa.x + pa.y);
;           const f2 sa2 = {sa, sa};
;           S0 = t0 + sa2 * b01; S1 = t1 + sa2 * b23;
;           f2 py = S0 * r01; py += S1 * r23;
;           pp[i] = py.x + py.y;
;           cur = nxt; nxt = nx2; nx2 = nx3;
;         }
;         const float tA = o1 ? pp[0] : pp[1], kA = o1 ? pp[1] : pp[0];
;         const float tB = o1 ? pp[2] : pp[3], kB = o1 ? pp[3] : pp[2];
;         const float r0 = kA + dppf<0xB1>(tA), r1 = kB + dppf<0xB1>(tB);
;         const float tC = o2 ? r0 : r1, kC = o2 ? r1 : r0;
;         float u = kC + dppf<0x4E>(tC);
;         u += dppf<0x124>(u);
;         u += dppf<0x128>(u);
;         yb[(g4 * 4 + (q & 3)) * 16 + rowl] = u;
;       }
	v_add_f32_dpp v108, v108, v108 quad_perm:[1,0,3,2] row_mask:0xf bank_mask:0xf bound_ctrl:1
	v_pk_mul_f32 v[14:15], v[14:15], v[88:89] op_sel_hi:[1,0]
	v_pk_mul_f32 v[12:13], v[12:13], v[88:89] op_sel_hi:[1,0]
	v_add_f32_dpp v108, v108, v108 quad_perm:[2,3,0,1] row_mask:0xf bank_mask:0xf bound_ctrl:1
	v_add_f32_dpp v75, v75, v75 quad_perm:[1,0,3,2] row_mask:0xf bank_mask:0xf bound_ctrl:1
	v_pk_fma_f32 v[64:65], v[64:65], v[10:11], v[14:15]
	v_pk_fma_f32 v[66:67], v[66:67], v[8:9], v[12:13]
	v_add_f32_dpp v75, v75, v75 quad_perm:[2,3,0,1] row_mask:0xf bank_mask:0xf bound_ctrl:1
	v_mov_b32_e32 v98, v91
	ds_write_b32 v73, v108 offset:256
	v_add_f32_dpp v75, v75, v75 row_half_mirror row_mask:0xf bank_mask:0xf bound_ctrl:1
	ds_read_b128 v[8:11], v72 offset:13184
	ds_read_b128 v[12:15], v72 offset:13440
	v_add_f32_dpp v96, v75, v75 row_mirror row_mask:0xf bank_mask:0xf bound_ctrl:1
	v_pk_fma_f32 v[64:65], v[6:7], v[96:97], v[64:65] op_sel_hi:[1,0,1]
	v_pk_fma_f32 v[66:67], v[4:5], v[96:97], v[66:67] op_sel_hi:[1,0,1]
	v_pk_mul_f32 v[18:19], v[18:19], v[64:65]
	v_pk_mul_f32 v[22:23], v[22:23], v[64:65]
	v_pk_mul_f32 v[36:37], v[36:37], v[66:67]
	v_pk_mul_f32 v[38:39], v[38:39], v[64:65]
	v_pk_fma_f32 v[64:65], v[16:17], v[66:67], v[18:19]
	v_pk_fma_f32 v[66:67], v[20:21], v[66:67], v[22:23]
	v_add_f32_e32 v75, v64, v65
	v_add_f32_e32 v64, v66, v67
	v_pk_fma_f32 v[36:37], v[28:29], v[88:89], v[36:37] op_sel:[0,1,0]
	v_pk_fma_f32 v[38:39], v[30:31], v[88:89], v[38:39] op_sel:[0,1,0]
	v_add_f32_dpp v64, v64, v64 quad_perm:[1,0,3,2] row_mask:0xf bank_mask:0xf bound_ctrl:1
	ds_read_b128 v[4:7], v72 offset:12928
	ds_read_b128 v[16:19], v72 offset:13696
	v_add_f32_dpp v64, v64, v64 quad_perm:[2,3,0,1] row_mask:0xf bank_mask:0xf bound_ctrl:1
	ds_read_b128 v[20:23], v72 offset:14080
	ds_read_b128 v[28:31], v72 offset:14848
	v_add_f32_dpp v64, v64, v64 row_half_mirror row_mask:0xf bank_mask:0xf bound_ctrl:1
	s_nop 1
	v_add_f32_dpp v64, v64, v64 row_mirror row_mask:0xf bank_mask:0xf bound_ctrl:1
	v_pk_fma_f32 v[66:67], v[24:25], v[64:65], v[36:37] op_sel_hi:[1,0,1]
	v_pk_fma_f32 v[64:65], v[26:27], v[64:65], v[38:39] op_sel_hi:[1,0,1]
	v_pk_mul_f32 v[88:89], v[48:49], v[66:67]
	v_pk_mul_f32 v[34:35], v[34:35], v[64:65]
	v_pk_mul_f32 v[42:43], v[42:43], v[64:65]
	v_pk_fma_f32 v[96:97], v[32:33], v[66:67], v[34:35]
	v_pk_fma_f32 v[66:67], v[40:41], v[66:67], v[42:43]
	v_pk_mul_f32 v[64:65], v[50:51], v[64:65]
	v_add_f32_e32 v66, v66, v67
	v_pk_fma_f32 v[88:89], v[52:53], v[90:91], v[88:89] op_sel_hi:[1,0,1]
	v_pk_fma_f32 v[64:65], v[54:55], v[90:91], v[64:65] op_sel_hi:[1,0,1]
	v_add_f32_dpp v66, v66, v66 quad_perm:[1,0,3,2] row_mask:0xf bank_mask:0xf bound_ctrl:1
	v_add_f32_e32 v90, v96, v97
	v_add_f32_dpp v105, v75, v75 row_ror:8 row_mask:0xf bank_mask:0x3 bound_ctrl:1
	v_add_f32_dpp v66, v66, v66 quad_perm:[2,3,0,1] row_mask:0xf bank_mask:0xf bound_ctrl:1
	v_add_f32_dpp v107, v90, v90 row_ror:8 row_mask:0xf bank_mask:0x3 bound_ctrl:1
	ds_read_b128 v[24:27], v72 offset:14336
	ds_read_b128 v[36:39], v72 offset:14592
	v_add_f32_dpp v66, v66, v66 row_half_mirror row_mask:0xf bank_mask:0xf bound_ctrl:1
	ds_read_b128 v[48:51], v72 offset:16000
	ds_read_b128 v[32:35], v72 offset:15104
	v_add_f32_dpp v66, v66, v66 row_mirror row_mask:0xf bank_mask:0xf bound_ctrl:1
	v_pk_fma_f32 v[64:65], v[46:47], v[66:67], v[64:65] op_sel_hi:[1,0,1]
	v_pk_fma_f32 v[88:89], v[44:45], v[66:67], v[88:89] op_sel_hi:[1,0,1]
	s_waitcnt lgkmcnt(11)
	v_pk_mul_f32 v[66:67], v[94:95], v[64:65]
	v_pk_mul_f32 v[58:59], v[58:59], v[64:65]
	v_pk_fma_f32 v[66:67], v[92:93], v[88:89], v[66:67]
	v_pk_mul_f32 v[64:65], v[78:79], v[64:65]
	v_add_f32_e32 v66, v66, v67
	v_pk_fma_f32 v[78:79], v[56:57], v[88:89], v[58:59]
	v_pk_mul_f32 v[76:77], v[76:77], v[88:89]
	v_add_f32_dpp v66, v66, v66 quad_perm:[1,0,3,2] row_mask:0xf bank_mask:0xf bound_ctrl:1
	v_pk_fma_f32 v[64:65], v[98:99], v[82:83], v[64:65] op_sel_hi:[0,1,1]
	v_add_f32_e32 v104, v78, v79
	v_add_f32_dpp v66, v66, v66 quad_perm:[2,3,0,1] row_mask:0xf bank_mask:0xf bound_ctrl:1
	v_pk_fma_f32 v[76:77], v[98:99], v[80:81], v[76:77] op_sel_hi:[0,1,1]
	ds_read_b128 v[40:43], v72 offset:15488
	ds_read_b128 v[52:55], v72 offset:16256
	v_add_f32_dpp v66, v66, v66 row_half_mirror row_mask:0xf bank_mask:0xf bound_ctrl:1
	ds_read_b128 v[44:47], v72 offset:15744
	ds_read_b128 v[56:59], v72 offset:16512
	v_add_f32_dpp v78, v66, v66 row_mirror row_mask:0xf bank_mask:0xf bound_ctrl:1
	v_pk_fma_f32 v[64:65], v[62:63], v[78:79], v[64:65] op_sel_hi:[1,0,1]
	v_pk_fma_f32 v[66:67], v[60:61], v[78:79], v[76:77] op_sel_hi:[1,0,1]
	v_pk_mul_f32 v[102:103], v[86:87], v[64:65]
	v_pk_fma_f32 v[102:103], v[84:85], v[66:67], v[102:103]
	s_waitcnt lgkmcnt(14)
	v_pk_mul_f32 v[2:3], v[64:65], v[2:3]
	v_add_f32_e32 v102, v102, v103
	ds_read_b128 v[60:63], v72 offset:17152
	v_add_f32_dpp v105, v104, v104 row_ror:8 row_mask:0xf bank_mask:0xc bound_ctrl:1
	ds_read_b128 v[76:79], v72 offset:17408
	ds_read_b128 v[80:83], v72 offset:17664
	ds_read_b128 v[84:87], v72 offset:17920
	ds_read_b128 v[88:91], v100 offset:48
	ds_read_b128 v[92:95], v72 offset:16896
	v_add_f32_dpp v107, v102, v102 row_ror:8 row_mask:0xf bank_mask:0xc bound_ctrl:1
	v_pk_fma_f32 v[96:97], v[66:67], v[0:1], v[2:3]
	v_add_f32_dpp v108, v105, v105 row_half_mirror row_mask:0xf bank_mask:0x5 bound_ctrl:1
	v_add_f32_dpp v108, v107, v107 row_half_mirror row_mask:0xf bank_mask:0xa bound_ctrl:1
	ds_read_b128 v[0:3], v72 offset:18304
	v_add_f32_e32 v75, v96, v97
	s_waitcnt lgkmcnt(2)
; template <int CTRL> DI float dppf(float v) { return __int_as_float(__builtin_amdgcn_update_dpp(0, __float_as_int(v), CTRL, 0xf, 0xf, false)); }
; DI float red16(float p) { p += dppf<0xB1>(p); p += dppf<0x4E>(p); p += dppf<0x141>(p); p += dppf<0x140>(p); return p; }
; DI void scan_task(const Params& P, int sb, unsigned char* lds) {
;     ...
;       for (int g4 = 0; g4 < CH / 4; ++g4) {
;         const float* gb = cb + g4 * 4 * SREC;
;         const float4 v4 = *(const float4*)(vrow + g4 * 4);
;         float pp[4];
; #pragma unroll
;         for (int i = 0; i < 4; ++i) {
;           ld_ops(nx3, gb + (i + 3) * SREC, q4);
;           const f2 a01 = {cur.a.x, cur.a.y}, a23 = {cur.a.z, cur.a.w}, w01 = {cur.w.x, cur.w.y}, w23 = {cur.w.z, cur.w.w};
;           const f2 k01 = {cur.k.x, cur.k.y}, k23 = {cur.k.z, cur.k.w}, b01 = {cur.b.x, cur.b.y}, b23 = {cur.b.z, cur.b.w};
;           const f2 r01 = {cur.r.x, cur.r.y}, r23 = {cur.r.z, cur.r.w};
;           f2 pa = S0 * a01; pa += S1 * a23;
;           const float vs = (i == 0) ? v4.x : (i == 1) ? v4.y : (i == 2) ? v4.z : v4.w;
;           const f2 vv = {vs, vs};
;           const f2 t0 = S0 * w01 + vv * k01, t1 = S1 * w23 + vv * k23;
;           const float sa = red16(pa.x + pa.y);
;           const f2 sa2 = {sa, sa};
;           S0 = t0 + sa2 * b01; S1 = t1 + sa2 * b23;
;           f2 py = S0 * r01; py += S1 * r23;
;           pp[i] = py.x + py.y;
;           cur = nxt; nxt = nx2; nx2 = nx3;
;         }
;         const float tA = o1 ? pp[0] : pp[1], kA = o1 ? pp[1] : pp[0];
;         const float tB = o1 ? pp[2] : pp[3], kB = o1 ? pp[3] : pp[2];
;         const float r0 = kA + dppf<0xB1>(tA), r1 = kB + dppf<0xB1>(tB);
;         const float tC = o2 ? r0 : r1, kC = o2 ? r1 : r0;
;         float u = kC + dppf<0x4E>(tC);
;         u += dppf<0x124>(u);
;         u += dppf<0x128>(u);
;         yb[(g4 * 4 + (q & 3)) * 16 + rowl] = u;
;       }
	v_add_f32_dpp v108, v108, v108 quad_perm:[1,0,3,2] row_mask:0xf bank_mask:0xf bound_ctrl:1
	v_pk_mul_f32 v[14:15], v[14:15], v[88:89] op_sel_hi:[1,0]
	v_pk_mul_f32 v[12:13], v[12:13], v[88:89] op_sel_hi:[1,0]
	v_add_f32_dpp v108, v108, v108 quad_perm:[2,3,0,1] row_mask:0xf bank_mask:0xf bound_ctrl:1
	v_add_f32_dpp v75, v75, v75 quad_perm:[1,0,3,2] row_mask:0xf bank_mask:0xf bound_ctrl:1
	v_pk_fma_f32 v[64:65], v[64:65], v[10:11], v[14:15]
	v_pk_fma_f32 v[66:67], v[66:67], v[8:9], v[12:13]
	v_add_f32_dpp v75, v75, v75 quad_perm:[2,3,0,1] row_mask:0xf bank_mask:0xf bound_ctrl:1
	v_mov_b32_e32 v98, v91
	ds_write_b32 v73, v108 offset:512
	v_add_f32_dpp v75, v75, v75 row_half_mirror row_mask:0xf bank_mask:0xf bound_ctrl:1
	ds_read_b128 v[8:11], v72 offset:18816
	ds_read_b128 v[12:15], v72 offset:19072
	v_add_f32_dpp v96, v75, v75 row_mirror row_mask:0xf bank_mask:0xf bound_ctrl:1
	v_pk_fma_f32 v[64:65], v[6:7], v[96:97], v[64:65] op_sel_hi:[1,0,1]
	v_pk_fma_f32 v[66:67], v[4:5], v[96:97], v[66:67] op_sel_hi:[1,0,1]
	v_pk_mul_f32 v[18:19], v[18:19], v[64:65]
	v_pk_mul_f32 v[22:23], v[22:23], v[64:65]
	v_pk_mul_f32 v[36:37], v[36:37], v[66:67]
	v_pk_mul_f32 v[38:39], v[38:39], v[64:65]
	v_pk_fma_f32 v[64:65], v[16:17], v[66:67], v[18:19]
	v_pk_fma_f32 v[66:67], v[20:21], v[66:67], v[22:23]
	v_add_f32_e32 v75, v64, v65
	v_add_f32_e32 v64, v66, v67
	v_pk_fma_f32 v[36:37], v[28:29], v[88:89], v[36:37] op_sel:[0,1,0]
	v_pk_fma_f32 v[38:39], v[30:31], v[88:89], v[38:39] op_sel:[0,1,0]
	v_add_f32_dpp v64, v64, v64 quad_perm:[1,0,3,2] row_mask:0xf bank_mask:0xf bound_ctrl:1
	ds_read_b128 v[4:7], v72 offset:18560
	ds_read_b128 v[16:19], v72 offset:19328
	v_add_f32_dpp v64, v64, v64 quad_perm:[2,3,0,1] row_mask:0xf bank_mask:0xf bound_ctrl:1
	ds_read_b128 v[20:23], v72 offset:19712
	ds_read_b128 v[28:31], v72 offset:20480
	v_add_f32_dpp v64, v64, v64 row_half_mirror row_mask:0xf bank_mask:0xf bound_ctrl:1
	s_nop 1
	v_add_f32_dpp v64, v64, v64 row_mirror row_mask:0xf bank_mask:0xf bound_ctrl:1
	v_pk_fma_f32 v[66:67], v[24:25], v[64:65], v[36:37] op_sel_hi:[1,0,1]
	v_pk_fma_f32 v[64:65], v[26:27], v[64:65], v[38:39] op_sel_hi:[1,0,1]
	v_pk_mul_f32 v[88:89], v[48:49], v[66:67]
	v_pk_mul_f32 v[34:35], v[34:35], v[64:65]
	v_pk_mul_f32 v[42:43], v[42:43], v[64:65]
	v_pk_fma_f32 v[96:97], v[32:33], v[66:67], v[34:35]
	v_pk_fma_f32 v[66:67], v[40:41], v[66:67], v[42:43]
	v_pk_mul_f32 v[64:65], v[50:51], v[64:65]
	v_add_f32_e32 v66, v66, v67
	v_pk_fma_f32 v[88:89], v[52:53], v[90:91], v[88:89] op_sel_hi:[1,0,1]
	v_pk_fma_f32 v[64:65], v[54:55], v[90:91], v[64:65] op_sel_hi:[1,0,1]
	v_add_f32_dpp v66, v66, v66 quad_perm:[1,0,3,2] row_mask:0xf bank_mask:0xf bound_ctrl:1
	v_add_f32_e32 v90, v96, v97
	v_add_f32_dpp v105, v75, v75 row_ror:8 row_mask:0xf bank_mask:0x3 bound_ctrl:1
	v_add_f32_dpp v66, v66, v66 quad_perm:[2,3,0,1] row_mask:0xf bank_mask:0xf bound_ctrl:1
	v_add_f32_dpp v107, v90, v90 row_ror:8 row_mask:0xf bank_mask:0x3 bound_ctrl:1
	ds_read_b128 v[24:27], v72 offset:19968
	ds_read_b128 v[36:39], v72 offset:20224
	v_add_f32_dpp v66, v66, v66 row_half_mirror row_mask:0xf bank_mask:0xf bound_ctrl:1
	ds_read_b128 v[48:51], v72 offset:21632
	ds_read_b128 v[32:35], v72 offset:20736
	v_add_f32_dpp v66, v66, v66 row_mirror row_mask:0xf bank_mask:0xf bound_ctrl:1
	v_pk_fma_f32 v[64:65], v[46:47], v[66:67], v[64:65] op_sel_hi:[1,0,1]
	v_pk_fma_f32 v[88:89], v[44:45], v[66:67], v[88:89] op_sel_hi:[1,0,1]
	s_waitcnt lgkmcnt(11)
	v_pk_mul_f32 v[66:67], v[94:95], v[64:65]
	v_pk_mul_f32 v[58:59], v[58:59], v[64:65]
	v_pk_fma_f32 v[66:67], v[92:93], v[88:89], v[66:67]
	v_pk_mul_f32 v[64:65], v[78:79], v[64:65]
	v_add_f32_e32 v66, v66, v67
	v_pk_fma_f32 v[78:79], v[56:57], v[88:89], v[58:59]
	v_pk_mul_f32 v[76:77], v[76:77], v[88:89]
	v_add_f32_dpp v66, v66, v66 quad_perm:[1,0,3,2] row_mask:0xf bank_mask:0xf bound_ctrl:1
	v_pk_fma_f32 v[64:65], v[98:99], v[82:83], v[64:65] op_sel_hi:[0,1,1]
	v_add_f32_e32 v104, v78, v79
	v_add_f32_dpp v66, v66, v66 quad_perm:[2,3,0,1] row_mask:0xf bank_mask:0xf bound_ctrl:1
	v_pk_fma_f32 v[76:77], v[98:99], v[80:81], v[76:77] op_sel_hi:[0,1,1]
	ds_read_b128 v[40:43], v72 offset:21120
	ds_read_b128 v[52:55], v72 offset:21888
	v_add_f32_dpp v66, v66, v66 row_half_mirror row_mask:0xf bank_mask:0xf bound_ctrl:1
	ds_read_b128 v[44:47], v72 offset:21376
	ds_read_b128 v[56:59], v72 offset:22144
	v_add_f32_dpp v78, v66, v66 row_mirror row_mask:0xf bank_mask:0xf bound_ctrl:1
	v_pk_fma_f32 v[64:65], v[62:63], v[78:79], v[64:65] op_sel_hi:[1,0,1]
	v_pk_fma_f32 v[66:67], v[60:61], v[78:79], v[76:77] op_sel_hi:[1,0,1]
	v_pk_mul_f32 v[102:103], v[86:87], v[64:65]
	v_pk_fma_f32 v[102:103], v[84:85], v[66:67], v[102:103]
	s_waitcnt lgkmcnt(14)
	v_pk_mul_f32 v[2:3], v[64:65], v[2:3]
	v_add_f32_e32 v102, v102, v103
	ds_read_b128 v[60:63], v72 offset:22784
	v_add_f32_dpp v105, v104, v104 row_ror:8 row_mask:0xf bank_mask:0xc bound_ctrl:1
	ds_read_b128 v[76:79], v72 offset:23040
	ds_read_b128 v[80:83], v72 offset:23296
	ds_read_b128 v[84:87], v72 offset:23552
	ds_read_b128 v[88:91], v100 offset:64
	ds_read_b128 v[92:95], v72 offset:22528
	v_add_f32_dpp v107, v102, v102 row_ror:8 row_mask:0xf bank_mask:0xc bound_ctrl:1
	v_pk_fma_f32 v[96:97], v[66:67], v[0:1], v[2:3]
	v_add_f32_dpp v108, v105, v105 row_half_mirror row_mask:0xf bank_mask:0x5 bound_ctrl:1
	v_add_f32_dpp v108, v107, v107 row_half_mirror row_mask:0xf bank_mask:0xa bound_ctrl:1
	ds_read_b128 v[0:3], v72 offset:23936
	v_add_f32_e32 v75, v96, v97
	s_waitcnt lgkmcnt(2)
; template <int CTRL> DI float dppf(float v) { return __int_as_float(__builtin_amdgcn_update_dpp(0, __float_as_int(v), CTRL, 0xf, 0xf, false)); }
; DI float red16(float p) { p += dppf<0xB1>(p); p += dppf<0x4E>(p); p += dppf<0x141>(p); p += dppf<0x140>(p); return p; }
; DI void scan_task(const Params& P, int sb, unsigned char* lds) {
;     ...
;       for (int g4 = 0; g4 < CH / 4; ++g4) {
;         const float* gb = cb + g4 * 4 * SREC;
;         const float4 v4 = *(const float4*)(vrow + g4 * 4);
;         float pp[4];
; #pragma unroll
;         for (int i = 0; i < 4; ++i) {
;           ld_ops(nx3, gb + (i + 3) * SREC, q4);
;           const f2 a01 = {cur.a.x, cur.a.y}, a23 = {cur.a.z, cur.a.w}, w01 = {cur.w.x, cur.w.y}, w23 = {cur.w.z, cur.w.w};
;           const f2 k01 = {cur.k.x, cur.k.y}, k23 = {cur.k.z, cur.k.w}, b01 = {cur.b.x, cur.b.y}, b23 = {cur.b.z, cur.b.w};
;           const f2 r01 = {cur.r.x, cur.r.y}, r23 = {cur.r.z, cur.r.w};
;           f2 pa = S0 * a01; pa += S1 * a23;
;           const float vs = (i == 0) ? v4.x : (i == 1) ? v4.y : (i == 2) ? v4.z : v4.w;
;           const f2 vv = {vs, vs};
;           const f2 t0 = S0 * w01 + vv * k01, t1 = S1 * w23 + vv * k23;
;           const float sa = red16(pa.x + pa.y);
;           const f2 sa2 = {sa, sa};
;           S0 = t0 + sa2 * b01; S1 = t1 + sa2 * b23;
;           f2 py = S0 * r01; py += S1 * r23;
;           pp[i] = py.x + py.y;
;           cur = nxt; nxt = nx2; nx2 = nx3;
;         }
;         const float tA = o1 ? pp[0] : pp[1], kA = o1 ? pp[1] : pp[0];
;         const float tB = o1 ? pp[2] : pp[3], kB = o1 ? pp[3] : pp[2];
;         const float r0 = kA + dppf<0xB1>(tA), r1 = kB + dppf<0xB1>(tB);
;         const float tC = o2 ? r0 : r1, kC = o2 ? r1 : r0;
;         float u = kC + dppf<0x4E>(tC);
;         u += dppf<0x124>(u);
;         u += dppf<0x128>(u);
;         yb[(g4 * 4 + (q & 3)) * 16 + rowl] = u;
;       }
	v_add_f32_dpp v108, v108, v108 quad_perm:[1,0,3,2] row_mask:0xf bank_mask:0xf bound_ctrl:1
	v_pk_mul_f32 v[14:15], v[14:15], v[88:89] op_sel_hi:[1,0]
	v_pk_mul_f32 v[12:13], v[12:13], v[88:89] op_sel_hi:[1,0]
	v_add_f32_dpp v108, v108, v108 quad_perm:[2,3,0,1] row_mask:0xf bank_mask:0xf bound_ctrl:1
	v_add_f32_dpp v75, v75, v75 quad_perm:[1,0,3,2] row_mask:0xf bank_mask:0xf bound_ctrl:1
	v_pk_fma_f32 v[64:65], v[64:65], v[10:11], v[14:15]
	v_pk_fma_f32 v[66:67], v[66:67], v[8:9], v[12:13]
	v_add_f32_dpp v75, v75, v75 quad_perm:[2,3,0,1] row_mask:0xf bank_mask:0xf bound_ctrl:1
	v_mov_b32_e32 v98, v91
	ds_write_b32 v73, v108 offset:768
	v_add_f32_dpp v75, v75, v75 row_half_mirror row_mask:0xf bank_mask:0xf bound_ctrl:1
	ds_read_b128 v[8:11], v72 offset:24448
	ds_read_b128 v[12:15], v72 offset:24704
	v_add_f32_dpp v96, v75, v75 row_mirror row_mask:0xf bank_mask:0xf bound_ctrl:1
	v_pk_fma_f32 v[64:65], v[6:7], v[96:97], v[64:65] op_sel_hi:[1,0,1]
	v_pk_fma_f32 v[66:67], v[4:5], v[96:97], v[66:67] op_sel_hi:[1,0,1]
	v_pk_mul_f32 v[18:19], v[18:19], v[64:65]
	v_pk_mul_f32 v[22:23], v[22:23], v[64:65]
	v_pk_mul_f32 v[36:37], v[36:37], v[66:67]
	v_pk_mul_f32 v[38:39], v[38:39], v[64:65]
	v_pk_fma_f32 v[64:65], v[16:17], v[66:67], v[18:19]
	v_pk_fma_f32 v[66:67], v[20:21], v[66:67], v[22:23]
	v_add_f32_e32 v75, v64, v65
	v_add_f32_e32 v64, v66, v67
	v_pk_fma_f32 v[36:37], v[28:29], v[88:89], v[36:37] op_sel:[0,1,0]
	v_pk_fma_f32 v[38:39], v[30:31], v[88:89], v[38:39] op_sel:[0,1,0]
	v_add_f32_dpp v64, v64, v64 quad_perm:[1,0,3,2] row_mask:0xf bank_mask:0xf bound_ctrl:1
	ds_read_b128 v[4:7], v72 offset:24192
	ds_read_b128 v[16:19], v72 offset:24960
	v_add_f32_dpp v64, v64, v64 quad_perm:[2,3,0,1] row_mask:0xf bank_mask:0xf bound_ctrl:1
	ds_read_b128 v[20:23], v72 offset:25344
	ds_read_b128 v[28:31], v72 offset:26112
	v_add_f32_dpp v64, v64, v64 row_half_mirror row_mask:0xf bank_mask:0xf bound_ctrl:1
	s_nop 1
	v_add_f32_dpp v64, v64, v64 row_mirror row_mask:0xf bank_mask:0xf bound_ctrl:1
	v_pk_fma_f32 v[66:67], v[24:25], v[64:65], v[36:37] op_sel_hi:[1,0,1]
	v_pk_fma_f32 v[64:65], v[26:27], v[64:65], v[38:39] op_sel_hi:[1,0,1]
	v_pk_mul_f32 v[88:89], v[48:49], v[66:67]
	v_pk_mul_f32 v[34:35], v[34:35], v[64:65]
	v_pk_mul_f32 v[42:43], v[42:43], v[64:65]
	v_pk_fma_f32 v[96:97], v[32:33], v[66:67], v[34:35]
	v_pk_fma_f32 v[66:67], v[40:41], v[66:67], v[42:43]
	v_pk_mul_f32 v[64:65], v[50:51], v[64:65]
	v_add_f32_e32 v66, v66, v67
	v_pk_fma_f32 v[88:89], v[52:53], v[90:91], v[88:89] op_sel_hi:[1,0,1]
	v_pk_fma_f32 v[64:65], v[54:55], v[90:91], v[64:65] op_sel_hi:[1,0,1]
	v_add_f32_dpp v66, v66, v66 quad_perm:[1,0,3,2] row_mask:0xf bank_mask:0xf bound_ctrl:1
	v_add_f32_e32 v90, v96, v97
	v_add_f32_dpp v105, v75, v75 row_ror:8 row_mask:0xf bank_mask:0x3 bound_ctrl:1
	v_add_f32_dpp v66, v66, v66 quad_perm:[2,3,0,1] row_mask:0xf bank_mask:0xf bound_ctrl:1
	v_add_f32_dpp v107, v90, v90 row_ror:8 row_mask:0xf bank_mask:0x3 bound_ctrl:1
	ds_read_b128 v[24:27], v72 offset:25600
	ds_read_b128 v[36:39], v72 offset:25856
	v_add_f32_dpp v66, v66, v66 row_half_mirror row_mask:0xf bank_mask:0xf bound_ctrl:1
	ds_read_b128 v[48:51], v72 offset:27264
	ds_read_b128 v[32:35], v72 offset:26368
	v_add_f32_dpp v66, v66, v66 row_mirror row_mask:0xf bank_mask:0xf bound_ctrl:1
	v_pk_fma_f32 v[64:65], v[46:47], v[66:67], v[64:65] op_sel_hi:[1,0,1]
	v_pk_fma_f32 v[88:89], v[44:45], v[66:67], v[88:89] op_sel_hi:[1,0,1]
	s_waitcnt lgkmcnt(11)
	v_pk_mul_f32 v[66:67], v[94:95], v[64:65]
	v_pk_mul_f32 v[58:59], v[58:59], v[64:65]
	v_pk_fma_f32 v[66:67], v[92:93], v[88:89], v[66:67]
	v_pk_mul_f32 v[64:65], v[78:79], v[64:65]
	v_add_f32_e32 v66, v66, v67
	v_pk_fma_f32 v[78:79], v[56:57], v[88:89], v[58:59]
	v_pk_mul_f32 v[76:77], v[76:77], v[88:89]
	v_add_f32_dpp v66, v66, v66 quad_perm:[1,0,3,2] row_mask:0xf bank_mask:0xf bound_ctrl:1
	v_pk_fma_f32 v[64:65], v[98:99], v[82:83], v[64:65] op_sel_hi:[0,1,1]
	v_add_f32_e32 v104, v78, v79
	v_add_f32_dpp v66, v66, v66 quad_perm:[2,3,0,1] row_mask:0xf bank_mask:0xf bound_ctrl:1
	v_pk_fma_f32 v[76:77], v[98:99], v[80:81], v[76:77] op_sel_hi:[0,1,1]
	ds_read_b128 v[40:43], v72 offset:26752
	ds_read_b128 v[52:55], v72 offset:27520
	v_add_f32_dpp v66, v66, v66 row_half_mirror row_mask:0xf bank_mask:0xf bound_ctrl:1
	ds_read_b128 v[44:47], v72 offset:27008
	ds_read_b128 v[56:59], v72 offset:27776
	v_add_f32_dpp v78, v66, v66 row_mirror row_mask:0xf bank_mask:0xf bound_ctrl:1
	v_pk_fma_f32 v[64:65], v[62:63], v[78:79], v[64:65] op_sel_hi:[1,0,1]
	v_pk_fma_f32 v[66:67], v[60:61], v[78:79], v[76:77] op_sel_hi:[1,0,1]
	v_pk_mul_f32 v[102:103], v[86:87], v[64:65]
	v_pk_fma_f32 v[102:103], v[84:85], v[66:67], v[102:103]
	s_waitcnt lgkmcnt(14)
	v_pk_mul_f32 v[2:3], v[64:65], v[2:3]
	v_add_f32_e32 v102, v102, v103
	ds_read_b128 v[60:63], v72 offset:28416
	v_add_f32_dpp v105, v104, v104 row_ror:8 row_mask:0xf bank_mask:0xc bound_ctrl:1
	ds_read_b128 v[76:79], v72 offset:28672
	ds_read_b128 v[80:83], v72 offset:28928
	ds_read_b128 v[84:87], v72 offset:29184
	ds_read_b128 v[88:91], v100 offset:80
	ds_read_b128 v[92:95], v72 offset:28160
	v_add_f32_dpp v107, v102, v102 row_ror:8 row_mask:0xf bank_mask:0xc bound_ctrl:1
	v_pk_fma_f32 v[96:97], v[66:67], v[0:1], v[2:3]
	v_add_f32_dpp v108, v105, v105 row_half_mirror row_mask:0xf bank_mask:0x5 bound_ctrl:1
	v_add_f32_dpp v108, v107, v107 row_half_mirror row_mask:0xf bank_mask:0xa bound_ctrl:1
	ds_read_b128 v[0:3], v72 offset:29568
	v_add_f32_e32 v75, v96, v97
	s_waitcnt lgkmcnt(2)
; template <int CTRL> DI float dppf(float v) { return __int_as_float(__builtin_amdgcn_update_dpp(0, __float_as_int(v), CTRL, 0xf, 0xf, false)); }
; DI float red16(float p) { p += dppf<0xB1>(p); p += dppf<0x4E>(p); p += dppf<0x141>(p); p += dppf<0x140>(p); return p; }
; DI void scan_task(const Params& P, int sb, unsigned char* lds) {
;     ...
;       for (int g4 = 0; g4 < CH / 4; ++g4) {
;         const float* gb = cb + g4 * 4 * SREC;
;         const float4 v4 = *(const float4*)(vrow + g4 * 4);
;         float pp[4];
; #pragma unroll
;         for (int i = 0; i < 4; ++i) {
;           ld_ops(nx3, gb + (i + 3) * SREC, q4);
;           const f2 a01 = {cur.a.x, cur.a.y}, a23 = {cur.a.z, cur.a.w}, w01 = {cur.w.x, cur.w.y}, w23 = {cur.w.z, cur.w.w};
;           const f2 k01 = {cur.k.x, cur.k.y}, k23 = {cur.k.z, cur.k.w}, b01 = {cur.b.x, cur.b.y}, b23 = {cur.b.z, cur.b.w};
;           const f2 r01 = {cur.r.x, cur.r.y}, r23 = {cur.r.z, cur.r.w};
;           f2 pa = S0 * a01; pa += S1 * a23;
;           const float vs = (i == 0) ? v4.x : (i == 1) ? v4.y : (i == 2) ? v4.z : v4.w;
;           const f2 vv = {vs, vs};
;           const f2 t0 = S0 * w01 + vv * k01, t1 = S1 * w23 + vv * k23;
;           const float sa = red16(pa.x + pa.y);
;           const f2 sa2 = {sa, sa};
;           S0 = t0 + sa2 * b01; S1 = t1 + sa2 * b23;
;           f2 py = S0 * r01; py += S1 * r23;
;           pp[i] = py.x + py.y;
;           cur = nxt; nxt = nx2; nx2 = nx3;
;         }
;         const float tA = o1 ? pp[0] : pp[1], kA = o1 ? pp[1] : pp[0];
;         const float tB = o1 ? pp[2] : pp[3], kB = o1 ? pp[3] : pp[2];
;         const float r0 = kA + dppf<0xB1>(tA), r1 = kB + dppf<0xB1>(tB);
;         const float tC = o2 ? r0 : r1, kC = o2 ? r1 : r0;
;         float u = kC + dppf<0x4E>(tC);
;         u += dppf<0x124>(u);
;         u += dppf<0x128>(u);
;         yb[(g4 * 4 + (q & 3)) * 16 + rowl] = u;
;       }
	v_add_f32_dpp v108, v108, v108 quad_perm:[1,0,3,2] row_mask:0xf bank_mask:0xf bound_ctrl:1
	v_pk_mul_f32 v[14:15], v[14:15], v[88:89] op_sel_hi:[1,0]
	v_pk_mul_f32 v[12:13], v[12:13], v[88:89] op_sel_hi:[1,0]
	v_add_f32_dpp v108, v108, v108 quad_perm:[2,3,0,1] row_mask:0xf bank_mask:0xf bound_ctrl:1
	v_add_f32_dpp v75, v75, v75 quad_perm:[1,0,3,2] row_mask:0xf bank_mask:0xf bound_ctrl:1
	v_pk_fma_f32 v[64:65], v[64:65], v[10:11], v[14:15]
	v_pk_fma_f32 v[66:67], v[66:67], v[8:9], v[12:13]
	v_add_f32_dpp v75, v75, v75 quad_perm:[2,3,0,1] row_mask:0xf bank_mask:0xf bound_ctrl:1
	v_mov_b32_e32 v98, v91
	ds_write_b32 v73, v108 offset:1024
	v_add_f32_dpp v75, v75, v75 row_half_mirror row_mask:0xf bank_mask:0xf bound_ctrl:1
	ds_read_b128 v[8:11], v72 offset:30080
	ds_read_b128 v[12:15], v72 offset:30336
	v_add_f32_dpp v96, v75, v75 row_mirror row_mask:0xf bank_mask:0xf bound_ctrl:1
	v_pk_fma_f32 v[64:65], v[6:7], v[96:97], v[64:65] op_sel_hi:[1,0,1]
	v_pk_fma_f32 v[66:67], v[4:5], v[96:97], v[66:67] op_sel_hi:[1,0,1]
	v_pk_mul_f32 v[18:19], v[18:19], v[64:65]
	v_pk_mul_f32 v[22:23], v[22:23], v[64:65]
	v_pk_mul_f32 v[36:37], v[36:37], v[66:67]
	v_pk_mul_f32 v[38:39], v[38:39], v[64:65]
	v_pk_fma_f32 v[64:65], v[16:17], v[66:67], v[18:19]
	v_pk_fma_f32 v[66:67], v[20:21], v[66:67], v[22:23]
	v_add_f32_e32 v75, v64, v65
	v_add_f32_e32 v64, v66, v67
	v_pk_fma_f32 v[36:37], v[28:29], v[88:89], v[36:37] op_sel:[0,1,0]
	v_pk_fma_f32 v[38:39], v[30:31], v[88:89], v[38:39] op_sel:[0,1,0]
	v_add_f32_dpp v64, v64, v64 quad_perm:[1,0,3,2] row_mask:0xf bank_mask:0xf bound_ctrl:1
	ds_read_b128 v[4:7], v72 offset:29824
	ds_read_b128 v[16:19], v72 offset:30592
	v_add_f32_dpp v64, v64, v64 quad_perm:[2,3,0,1] row_mask:0xf bank_mask:0xf bound_ctrl:1
	ds_read_b128 v[20:23], v72 offset:30976
	ds_read_b128 v[28:31], v72 offset:31744
	v_add_f32_dpp v64, v64, v64 row_half_mirror row_mask:0xf bank_mask:0xf bound_ctrl:1
	s_nop 1
	v_add_f32_dpp v64, v64, v64 row_mirror row_mask:0xf bank_mask:0xf bound_ctrl:1
	v_pk_fma_f32 v[66:67], v[24:25], v[64:65], v[36:37] op_sel_hi:[1,0,1]
	v_pk_fma_f32 v[64:65], v[26:27], v[64:65], v[38:39] op_sel_hi:[1,0,1]
	v_pk_mul_f32 v[88:89], v[48:49], v[66:67]
	v_pk_mul_f32 v[34:35], v[34:35], v[64:65]
	v_pk_mul_f32 v[42:43], v[42:43], v[64:65]
	v_pk_fma_f32 v[96:97], v[32:33], v[66:67], v[34:35]
	v_pk_fma_f32 v[66:67], v[40:41], v[66:67], v[42:43]
	v_pk_mul_f32 v[64:65], v[50:51], v[64:65]
	v_add_f32_e32 v66, v66, v67
	v_pk_fma_f32 v[88:89], v[52:53], v[90:91], v[88:89] op_sel_hi:[1,0,1]
	v_pk_fma_f32 v[64:65], v[54:55], v[90:91], v[64:65] op_sel_hi:[1,0,1]
	v_add_f32_dpp v66, v66, v66 quad_perm:[1,0,3,2] row_mask:0xf bank_mask:0xf bound_ctrl:1
	v_add_f32_e32 v90, v96, v97
	v_add_f32_dpp v105, v75, v75 row_ror:8 row_mask:0xf bank_mask:0x3 bound_ctrl:1
	v_add_f32_dpp v66, v66, v66 quad_perm:[2,3,0,1] row_mask:0xf bank_mask:0xf bound_ctrl:1
	v_add_f32_dpp v107, v90, v90 row_ror:8 row_mask:0xf bank_mask:0x3 bound_ctrl:1
	ds_read_b128 v[24:27], v72 offset:31232
	ds_read_b128 v[36:39], v72 offset:31488
	v_add_f32_dpp v66, v66, v66 row_half_mirror row_mask:0xf bank_mask:0xf bound_ctrl:1
	ds_read_b128 v[48:51], v72 offset:32896
	ds_read_b128 v[32:35], v72 offset:32000
	v_add_f32_dpp v66, v66, v66 row_mirror row_mask:0xf bank_mask:0xf bound_ctrl:1
	v_pk_fma_f32 v[64:65], v[46:47], v[66:67], v[64:65] op_sel_hi:[1,0,1]
	v_pk_fma_f32 v[88:89], v[44:45], v[66:67], v[88:89] op_sel_hi:[1,0,1]
	s_waitcnt lgkmcnt(11)
	v_pk_mul_f32 v[66:67], v[94:95], v[64:65]
	v_pk_mul_f32 v[58:59], v[58:59], v[64:65]
	v_pk_fma_f32 v[66:67], v[92:93], v[88:89], v[66:67]
	v_pk_mul_f32 v[64:65], v[78:79], v[64:65]
	v_add_f32_e32 v66, v66, v67
	v_pk_fma_f32 v[78:79], v[56:57], v[88:89], v[58:59]
	v_pk_mul_f32 v[76:77], v[76:77], v[88:89]
	v_add_f32_dpp v66, v66, v66 quad_perm:[1,0,3,2] row_mask:0xf bank_mask:0xf bound_ctrl:1
	v_pk_fma_f32 v[64:65], v[98:99], v[82:83], v[64:65] op_sel_hi:[0,1,1]
	v_add_f32_e32 v104, v78, v79
	v_add_f32_dpp v66, v66, v66 quad_perm:[2,3,0,1] row_mask:0xf bank_mask:0xf bound_ctrl:1
	v_pk_fma_f32 v[76:77], v[98:99], v[80:81], v[76:77] op_sel_hi:[0,1,1]
	ds_read_b128 v[40:43], v72 offset:32384
	ds_read_b128 v[52:55], v72 offset:33152
	v_add_f32_dpp v66, v66, v66 row_half_mirror row_mask:0xf bank_mask:0xf bound_ctrl:1
	ds_read_b128 v[44:47], v72 offset:32640
	ds_read_b128 v[56:59], v72 offset:33408
	v_add_f32_dpp v78, v66, v66 row_mirror row_mask:0xf bank_mask:0xf bound_ctrl:1
	v_pk_fma_f32 v[64:65], v[62:63], v[78:79], v[64:65] op_sel_hi:[1,0,1]
	v_pk_fma_f32 v[66:67], v[60:61], v[78:79], v[76:77] op_sel_hi:[1,0,1]
	v_pk_mul_f32 v[102:103], v[86:87], v[64:65]
	v_pk_fma_f32 v[102:103], v[84:85], v[66:67], v[102:103]
	s_waitcnt lgkmcnt(14)
	v_pk_mul_f32 v[2:3], v[64:65], v[2:3]
	v_add_f32_e32 v102, v102, v103
	ds_read_b128 v[60:63], v72 offset:34048
	v_add_f32_dpp v105, v104, v104 row_ror:8 row_mask:0xf bank_mask:0xc bound_ctrl:1
	ds_read_b128 v[76:79], v72 offset:34304
	ds_read_b128 v[80:83], v72 offset:34560
	ds_read_b128 v[84:87], v72 offset:34816
	ds_read_b128 v[88:91], v100 offset:96
	ds_read_b128 v[92:95], v72 offset:33792
	v_add_f32_dpp v107, v102, v102 row_ror:8 row_mask:0xf bank_mask:0xc bound_ctrl:1
	v_pk_fma_f32 v[96:97], v[66:67], v[0:1], v[2:3]
	v_add_f32_dpp v108, v105, v105 row_half_mirror row_mask:0xf bank_mask:0x5 bound_ctrl:1
	v_add_f32_dpp v108, v107, v107 row_half_mirror row_mask:0xf bank_mask:0xa bound_ctrl:1
	ds_read_b128 v[0:3], v72 offset:35200
	v_add_f32_e32 v75, v96, v97
	s_waitcnt lgkmcnt(2)
; template <int CTRL> DI float dppf(float v) { return __int_as_float(__builtin_amdgcn_update_dpp(0, __float_as_int(v), CTRL, 0xf, 0xf, false)); }
; DI float red16(float p) { p += dppf<0xB1>(p); p += dppf<0x4E>(p); p += dppf<0x141>(p); p += dppf<0x140>(p); return p; }
; DI void scan_task(const Params& P, int sb, unsigned char* lds) {
;     ...
;       for (int g4 = 0; g4 < CH / 4; ++g4) {
;         const float* gb = cb + g4 * 4 * SREC;
;         const float4 v4 = *(const float4*)(vrow + g4 * 4);
;         float pp[4];
; #pragma unroll
;         for (int i = 0; i < 4; ++i) {
;           ld_ops(nx3, gb + (i + 3) * SREC, q4);
;           const f2 a01 = {cur.a.x, cur.a.y}, a23 = {cur.a.z, cur.a.w}, w01 = {cur.w.x, cur.w.y}, w23 = {cur.w.z, cur.w.w};
;           const f2 k01 = {cur.k.x, cur.k.y}, k23 = {cur.k.z, cur.k.w}, b01 = {cur.b.x, cur.b.y}, b23 = {cur.b.z, cur.b.w};
;           const f2 r01 = {cur.r.x, cur.r.y}, r23 = {cur.r.z, cur.r.w};
;           f2 pa = S0 * a01; pa += S1 * a23;
;           const float vs = (i == 0) ? v4.x : (i == 1) ? v4.y : (i == 2) ? v4.z : v4.w;
;           const f2 vv = {vs, vs};
;           const f2 t0 = S0 * w01 + vv * k01, t1 = S1 * w23 + vv * k23;
;           const float sa = red16(pa.x + pa.y);
;           const f2 sa2 = {sa, sa};
;           S0 = t0 + sa2 * b01; S1 = t1 + sa2 * b23;
;           f2 py = S0 * r01; py += S1 * r23;
;           pp[i] = py.x + py.y;
;           cur = nxt; nxt = nx2; nx2 = nx3;
;         }
;         const float tA = o1 ? pp[0] : pp[1], kA = o1 ? pp[1] : pp[0];
;         const float tB = o1 ? pp[2] : pp[3], kB = o1 ? pp[3] : pp[2];
;         const float r0 = kA + dppf<0xB1>(tA), r1 = kB + dppf<0xB1>(tB);
;         const float tC = o2 ? r0 : r1, kC = o2 ? r1 : r0;
;         float u = kC + dppf<0x4E>(tC);
;         u += dppf<0x124>(u);
;         u += dppf<0x128>(u);
;         yb[(g4 * 4 + (q & 3)) * 16 + rowl] = u;
;       }
	v_add_f32_dpp v108, v108, v108 quad_perm:[1,0,3,2] row_mask:0xf bank_mask:0xf bound_ctrl:1
	v_pk_mul_f32 v[14:15], v[14:15], v[88:89] op_sel_hi:[1,0]
	v_pk_mul_f32 v[12:13], v[12:13], v[88:89] op_sel_hi:[1,0]
	v_add_f32_dpp v108, v108, v108 quad_perm:[2,3,0,1] row_mask:0xf bank_mask:0xf bound_ctrl:1
	v_add_f32_dpp v75, v75, v75 quad_perm:[1,0,3,2] row_mask:0xf bank_mask:0xf bound_ctrl:1
	v_pk_fma_f32 v[64:65], v[64:65], v[10:11], v[14:15]
	v_pk_fma_f32 v[66:67], v[66:67], v[8:9], v[12:13]
	v_add_f32_dpp v75, v75, v75 quad_perm:[2,3,0,1] row_mask:0xf bank_mask:0xf bound_ctrl:1
	v_mov_b32_e32 v98, v91
	ds_write_b32 v73, v108 offset:1280
	v_add_f32_dpp v75, v75, v75 row_half_mirror row_mask:0xf bank_mask:0xf bound_ctrl:1
	ds_read_b128 v[8:11], v72 offset:35712
	ds_read_b128 v[12:15], v72 offset:35968
	v_add_f32_dpp v96, v75, v75 row_mirror row_mask:0xf bank_mask:0xf bound_ctrl:1
	v_pk_fma_f32 v[64:65], v[6:7], v[96:97], v[64:65] op_sel_hi:[1,0,1]
	v_pk_fma_f32 v[66:67], v[4:5], v[96:97], v[66:67] op_sel_hi:[1,0,1]
	v_pk_mul_f32 v[18:19], v[18:19], v[64:65]
	v_pk_mul_f32 v[22:23], v[22:23], v[64:65]
	v_pk_mul_f32 v[36:37], v[36:37], v[66:67]
	v_pk_mul_f32 v[38:39], v[38:39], v[64:65]
	v_pk_fma_f32 v[64:65], v[16:17], v[66:67], v[18:19]
	v_pk_fma_f32 v[66:67], v[20:21], v[66:67], v[22:23]
	v_add_f32_e32 v75, v64, v65
	v_add_f32_e32 v64, v66, v67
	v_pk_fma_f32 v[36:37], v[28:29], v[88:89], v[36:37] op_sel:[0,1,0]
	v_pk_fma_f32 v[38:39], v[30:31], v[88:89], v[38:39] op_sel:[0,1,0]
	v_add_f32_dpp v64, v64, v64 quad_perm:[1,0,3,2] row_mask:0xf bank_mask:0xf bound_ctrl:1
	ds_read_b128 v[4:7], v72 offset:35456
	ds_read_b128 v[16:19], v72 offset:36224
	v_add_f32_dpp v64, v64, v64 quad_perm:[2,3,0,1] row_mask:0xf bank_mask:0xf bound_ctrl:1
	ds_read_b128 v[20:23], v72 offset:36608
	ds_read_b128 v[28:31], v72 offset:37376
	v_add_f32_dpp v64, v64, v64 row_half_mirror row_mask:0xf bank_mask:0xf bound_ctrl:1
	s_nop 1
	v_add_f32_dpp v64, v64, v64 row_mirror row_mask:0xf bank_mask:0xf bound_ctrl:1
	v_pk_fma_f32 v[66:67], v[24:25], v[64:65], v[36:37] op_sel_hi:[1,0,1]
	v_pk_fma_f32 v[64:65], v[26:27], v[64:65], v[38:39] op_sel_hi:[1,0,1]
	v_pk_mul_f32 v[88:89], v[48:49], v[66:67]
	v_pk_mul_f32 v[34:35], v[34:35], v[64:65]
	v_pk_mul_f32 v[42:43], v[42:43], v[64:65]
	v_pk_fma_f32 v[96:97], v[32:33], v[66:67], v[34:35]
	v_pk_fma_f32 v[66:67], v[40:41], v[66:67], v[42:43]
	v_pk_mul_f32 v[64:65], v[50:51], v[64:65]
	v_add_f32_e32 v66, v66, v67
	v_pk_fma_f32 v[88:89], v[52:53], v[90:91], v[88:89] op_sel_hi:[1,0,1]
	v_pk_fma_f32 v[64:65], v[54:55], v[90:91], v[64:65] op_sel_hi:[1,0,1]
	v_add_f32_dpp v66, v66, v66 quad_perm:[1,0,3,2] row_mask:0xf bank_mask:0xf bound_ctrl:1
	v_add_f32_e32 v90, v96, v97
	v_add_f32_dpp v105, v75, v75 row_ror:8 row_mask:0xf bank_mask:0x3 bound_ctrl:1
	v_add_f32_dpp v66, v66, v66 quad_perm:[2,3,0,1] row_mask:0xf bank_mask:0xf bound_ctrl:1
	v_add_f32_dpp v107, v90, v90 row_ror:8 row_mask:0xf bank_mask:0x3 bound_ctrl:1
	ds_read_b128 v[24:27], v72 offset:36864
	ds_read_b128 v[36:39], v72 offset:37120
	v_add_f32_dpp v66, v66, v66 row_half_mirror row_mask:0xf bank_mask:0xf bound_ctrl:1
	ds_read_b128 v[48:51], v72 offset:38528
	ds_read_b128 v[32:35], v72 offset:37632
	v_add_f32_dpp v66, v66, v66 row_mirror row_mask:0xf bank_mask:0xf bound_ctrl:1
	v_pk_fma_f32 v[64:65], v[46:47], v[66:67], v[64:65] op_sel_hi:[1,0,1]
	v_pk_fma_f32 v[88:89], v[44:45], v[66:67], v[88:89] op_sel_hi:[1,0,1]
	s_waitcnt lgkmcnt(11)
	v_pk_mul_f32 v[66:67], v[94:95], v[64:65]
	v_pk_mul_f32 v[58:59], v[58:59], v[64:65]
	v_pk_fma_f32 v[66:67], v[92:93], v[88:89], v[66:67]
	v_pk_mul_f32 v[64:65], v[78:79], v[64:65]
	v_add_f32_e32 v66, v66, v67
	v_pk_fma_f32 v[78:79], v[56:57], v[88:89], v[58:59]
	v_pk_mul_f32 v[76:77], v[76:77], v[88:89]
	v_add_f32_dpp v66, v66, v66 quad_perm:[1,0,3,2] row_mask:0xf bank_mask:0xf bound_ctrl:1
	v_pk_fma_f32 v[64:65], v[98:99], v[82:83], v[64:65] op_sel_hi:[0,1,1]
	v_add_f32_e32 v104, v78, v79
	v_add_f32_dpp v66, v66, v66 quad_perm:[2,3,0,1] row_mask:0xf bank_mask:0xf bound_ctrl:1
	v_pk_fma_f32 v[76:77], v[98:99], v[80:81], v[76:77] op_sel_hi:[0,1,1]
	ds_read_b128 v[40:43], v72 offset:38016
	ds_read_b128 v[52:55], v72 offset:38784
	v_add_f32_dpp v66, v66, v66 row_half_mirror row_mask:0xf bank_mask:0xf bound_ctrl:1
	ds_read_b128 v[44:47], v72 offset:38272
	ds_read_b128 v[56:59], v72 offset:39040
	v_add_f32_dpp v78, v66, v66 row_mirror row_mask:0xf bank_mask:0xf bound_ctrl:1
	v_pk_fma_f32 v[64:65], v[62:63], v[78:79], v[64:65] op_sel_hi:[1,0,1]
	v_pk_fma_f32 v[66:67], v[60:61], v[78:79], v[76:77] op_sel_hi:[1,0,1]
	v_pk_mul_f32 v[102:103], v[86:87], v[64:65]
	v_pk_fma_f32 v[102:103], v[84:85], v[66:67], v[102:103]
	s_waitcnt lgkmcnt(14)
	v_pk_mul_f32 v[2:3], v[64:65], v[2:3]
	v_add_f32_e32 v102, v102, v103
	ds_read_b128 v[60:63], v72 offset:39680
	v_add_f32_dpp v105, v104, v104 row_ror:8 row_mask:0xf bank_mask:0xc bound_ctrl:1
	ds_read_b128 v[76:79], v72 offset:39936
	ds_read_b128 v[80:83], v72 offset:40192
	ds_read_b128 v[84:87], v72 offset:40448
	ds_read_b128 v[88:91], v100 offset:112
	ds_read_b128 v[92:95], v72 offset:39424
	v_add_f32_dpp v107, v102, v102 row_ror:8 row_mask:0xf bank_mask:0xc bound_ctrl:1
	v_pk_fma_f32 v[96:97], v[66:67], v[0:1], v[2:3]
	v_add_f32_dpp v108, v105, v105 row_half_mirror row_mask:0xf bank_mask:0x5 bound_ctrl:1
	v_add_f32_dpp v108, v107, v107 row_half_mirror row_mask:0xf bank_mask:0xa bound_ctrl:1
	ds_read_b128 v[0:3], v72 offset:40832
	v_add_f32_e32 v75, v96, v97
	s_waitcnt lgkmcnt(2)
; template <int CTRL> DI float dppf(float v) { return __int_as_float(__builtin_amdgcn_update_dpp(0, __float_as_int(v), CTRL, 0xf, 0xf, false)); }
; DI float red16(float p) { p += dppf<0xB1>(p); p += dppf<0x4E>(p); p += dppf<0x141>(p); p += dppf<0x140>(p); return p; }
; DI void scan_task(const Params& P, int sb, unsigned char* lds) {
;     ...
;       for (int g4 = 0; g4 < CH / 4; ++g4) {
;         const float* gb = cb + g4 * 4 * SREC;
;         const float4 v4 = *(const float4*)(vrow + g4 * 4);
;         float pp[4];
; #pragma unroll
;         for (int i = 0; i < 4; ++i) {
;           ld_ops(nx3, gb + (i + 3) * SREC, q4);
;           const f2 a01 = {cur.a.x, cur.a.y}, a23 = {cur.a.z, cur.a.w}, w01 = {cur.w.x, cur.w.y}, w23 = {cur.w.z, cur.w.w};
;           const f2 k01 = {cur.k.x, cur.k.y}, k23 = {cur.k.z, cur.k.w}, b01 = {cur.b.x, cur.b.y}, b23 = {cur.b.z, cur.b.w};
;           const f2 r01 = {cur.r.x, cur.r.y}, r23 = {cur.r.z, cur.r.w};
;           f2 pa = S0 * a01; pa += S1 * a23;
;           const float vs = (i == 0) ? v4.x : (i == 1) ? v4.y : (i == 2) ? v4.z : v4.w;
;           const f2 vv = {vs, vs};
;           const f2 t0 = S0 * w01 + vv * k01, t1 = S1 * w23 + vv * k23;
;           const float sa = red16(pa.x + pa.y);
;           const f2 sa2 = {sa, sa};
;           S0 = t0 + sa2 * b01; S1 = t1 + sa2 * b23;
;           f2 py = S0 * r01; py += S1 * r23;
;           pp[i] = py.x + py.y;
;           cur = nxt; nxt = nx2; nx2 = nx3;
;         }
;         const float tA = o1 ? pp[0] : pp[1], kA = o1 ? pp[1] : pp[0];
;         const float tB = o1 ? pp[2] : pp[3], kB = o1 ? pp[3] : pp[2];
;         const float r0 = kA + dppf<0xB1>(tA), r1 = kB + dppf<0xB1>(tB);
;         const float tC = o2 ? r0 : r1, kC = o2 ? r1 : r0;
;         float u = kC + dppf<0x4E>(tC);
;         u += dppf<0x124>(u);
;         u += dppf<0x128>(u);
;         yb[(g4 * 4 + (q & 3)) * 16 + rowl] = u;
;       }
;       __syncthreads();
;     }
	v_add_f32_dpp v108, v108, v108 quad_perm:[1,0,3,2] row_mask:0xf bank_mask:0xf bound_ctrl:1
	v_pk_mul_f32 v[14:15], v[14:15], v[88:89] op_sel_hi:[1,0]
	v_pk_mul_f32 v[12:13], v[12:13], v[88:89] op_sel_hi:[1,0]
	v_add_f32_dpp v108, v108, v108 quad_perm:[2,3,0,1] row_mask:0xf bank_mask:0xf bound_ctrl:1
	v_add_f32_dpp v75, v75, v75 quad_perm:[1,0,3,2] row_mask:0xf bank_mask:0xf bound_ctrl:1
	v_pk_fma_f32 v[64:65], v[64:65], v[10:11], v[14:15]
	v_pk_fma_f32 v[66:67], v[66:67], v[8:9], v[12:13]
	v_add_f32_dpp v75, v75, v75 quad_perm:[2,3,0,1] row_mask:0xf bank_mask:0xf bound_ctrl:1
	v_mov_b32_e32 v98, v91
	ds_write_b32 v73, v108 offset:1536
	v_add_f32_dpp v75, v75, v75 row_half_mirror row_mask:0xf bank_mask:0xf bound_ctrl:1
	ds_read_b128 v[8:11], v72 offset:41344
	ds_read_b128 v[12:15], v72 offset:41600
	v_add_f32_dpp v96, v75, v75 row_mirror row_mask:0xf bank_mask:0xf bound_ctrl:1
	v_pk_fma_f32 v[64:65], v[6:7], v[96:97], v[64:65] op_sel_hi:[1,0,1]
	v_pk_fma_f32 v[66:67], v[4:5], v[96:97], v[66:67] op_sel_hi:[1,0,1]
	v_pk_mul_f32 v[18:19], v[18:19], v[64:65]
	v_pk_mul_f32 v[22:23], v[22:23], v[64:65]
	v_pk_mul_f32 v[36:37], v[36:37], v[66:67]
	v_pk_mul_f32 v[38:39], v[38:39], v[64:65]
	v_pk_fma_f32 v[64:65], v[16:17], v[66:67], v[18:19]
	v_pk_fma_f32 v[66:67], v[20:21], v[66:67], v[22:23]
	v_add_f32_e32 v75, v64, v65
	v_add_f32_e32 v64, v66, v67
	v_pk_fma_f32 v[36:37], v[28:29], v[88:89], v[36:37] op_sel:[0,1,0]
	v_pk_fma_f32 v[38:39], v[30:31], v[88:89], v[38:39] op_sel:[0,1,0]
	v_add_f32_dpp v64, v64, v64 quad_perm:[1,0,3,2] row_mask:0xf bank_mask:0xf bound_ctrl:1
	ds_read_b128 v[4:7], v72 offset:41088
	ds_read_b128 v[16:19], v72 offset:41856
	v_add_f32_dpp v64, v64, v64 quad_perm:[2,3,0,1] row_mask:0xf bank_mask:0xf bound_ctrl:1
	ds_read_b128 v[20:23], v72 offset:42240
	ds_read_b128 v[28:31], v72 offset:43008
	v_add_f32_dpp v64, v64, v64 row_half_mirror row_mask:0xf bank_mask:0xf bound_ctrl:1
	s_nop 1
	v_add_f32_dpp v64, v64, v64 row_mirror row_mask:0xf bank_mask:0xf bound_ctrl:1
	v_pk_fma_f32 v[66:67], v[24:25], v[64:65], v[36:37] op_sel_hi:[1,0,1]
	v_pk_fma_f32 v[64:65], v[26:27], v[64:65], v[38:39] op_sel_hi:[1,0,1]
	v_pk_mul_f32 v[88:89], v[48:49], v[66:67]
	v_pk_mul_f32 v[34:35], v[34:35], v[64:65]
	v_pk_mul_f32 v[42:43], v[42:43], v[64:65]
	v_pk_fma_f32 v[96:97], v[32:33], v[66:67], v[34:35]
	v_pk_fma_f32 v[66:67], v[40:41], v[66:67], v[42:43]
	v_pk_mul_f32 v[64:65], v[50:51], v[64:65]
	v_add_f32_e32 v66, v66, v67
	v_pk_fma_f32 v[88:89], v[52:53], v[90:91], v[88:89] op_sel_hi:[1,0,1]
	v_pk_fma_f32 v[64:65], v[54:55], v[90:91], v[64:65] op_sel_hi:[1,0,1]
	v_add_f32_dpp v66, v66, v66 quad_perm:[1,0,3,2] row_mask:0xf bank_mask:0xf bound_ctrl:1
	v_add_f32_e32 v90, v96, v97
	v_add_f32_dpp v105, v75, v75 row_ror:8 row_mask:0xf bank_mask:0x3 bound_ctrl:1
	v_add_f32_dpp v66, v66, v66 quad_perm:[2,3,0,1] row_mask:0xf bank_mask:0xf bound_ctrl:1
	v_add_f32_dpp v107, v90, v90 row_ror:8 row_mask:0xf bank_mask:0x3 bound_ctrl:1
	ds_read_b128 v[24:27], v72 offset:42496
	ds_read_b128 v[36:39], v72 offset:42752
	v_add_f32_dpp v66, v66, v66 row_half_mirror row_mask:0xf bank_mask:0xf bound_ctrl:1
	ds_read_b128 v[48:51], v72 offset:44160
	ds_read_b128 v[32:35], v72 offset:43264
	v_add_f32_dpp v66, v66, v66 row_mirror row_mask:0xf bank_mask:0xf bound_ctrl:1
	v_pk_fma_f32 v[64:65], v[46:47], v[66:67], v[64:65] op_sel_hi:[1,0,1]
	v_pk_fma_f32 v[88:89], v[44:45], v[66:67], v[88:89] op_sel_hi:[1,0,1]
	s_waitcnt lgkmcnt(11)
	v_pk_mul_f32 v[66:67], v[94:95], v[64:65]
	v_pk_mul_f32 v[58:59], v[58:59], v[64:65]
	v_pk_fma_f32 v[66:67], v[92:93], v[88:89], v[66:67]
	v_pk_mul_f32 v[64:65], v[78:79], v[64:65]
	v_add_f32_e32 v66, v66, v67
	v_pk_fma_f32 v[78:79], v[56:57], v[88:89], v[58:59]
	v_pk_mul_f32 v[76:77], v[76:77], v[88:89]
	v_add_f32_dpp v66, v66, v66 quad_perm:[1,0,3,2] row_mask:0xf bank_mask:0xf bound_ctrl:1
	v_pk_fma_f32 v[64:65], v[98:99], v[82:83], v[64:65] op_sel_hi:[0,1,1]
	v_add_f32_e32 v104, v78, v79
	v_add_f32_dpp v66, v66, v66 quad_perm:[2,3,0,1] row_mask:0xf bank_mask:0xf bound_ctrl:1
	v_pk_fma_f32 v[76:77], v[98:99], v[80:81], v[76:77] op_sel_hi:[0,1,1]
	ds_read_b128 v[40:43], v72 offset:43648
	ds_read_b128 v[52:55], v72 offset:44416
	v_add_f32_dpp v66, v66, v66 row_half_mirror row_mask:0xf bank_mask:0xf bound_ctrl:1
	ds_read_b128 v[44:47], v72 offset:43904
	ds_read_b128 v[56:59], v72 offset:44672
	v_add_f32_dpp v78, v66, v66 row_mirror row_mask:0xf bank_mask:0xf bound_ctrl:1
	v_pk_fma_f32 v[64:65], v[62:63], v[78:79], v[64:65] op_sel_hi:[1,0,1]
	v_pk_fma_f32 v[66:67], v[60:61], v[78:79], v[76:77] op_sel_hi:[1,0,1]
	v_pk_mul_f32 v[102:103], v[86:87], v[64:65]
	v_pk_fma_f32 v[102:103], v[84:85], v[66:67], v[102:103]
	s_nop 0
	v_add_f32_e32 v102, v102, v103
	v_add_f32_dpp v105, v104, v104 row_ror:8 row_mask:0xf bank_mask:0xc bound_ctrl:1
	s_nop 1
	v_add_f32_dpp v107, v102, v102 row_ror:8 row_mask:0xf bank_mask:0xc bound_ctrl:1
	v_add_f32_dpp v108, v105, v105 row_half_mirror row_mask:0xf bank_mask:0x5 bound_ctrl:1
	s_nop 1
	v_add_f32_dpp v108, v107, v107 row_half_mirror row_mask:0xf bank_mask:0xa bound_ctrl:1
	s_nop 1
	v_add_f32_dpp v108, v108, v108 quad_perm:[1,0,3,2] row_mask:0xf bank_mask:0xf bound_ctrl:1
	s_nop 1
	v_add_f32_dpp v108, v108, v108 quad_perm:[2,3,0,1] row_mask:0xf bank_mask:0xf bound_ctrl:1
	ds_write_b32 v73, v108 offset:1792
	s_add_i32 s0, s0, 1
	s_xor_b64 s[6:7], s[6:7], -1
	s_cmpk_eq_i32 s0, 0x108
	s_waitcnt lgkmcnt(0)
	s_barrier
	s_cbranch_scc0 .LBB0_1197
	s_mov_b64 s[4:5], 0
